# attention q-subtile loop: qn loads issued before next-subtile prefetch, counted vmcnt
# speedup vs baseline: 1.0062x; 1.0062x over previous
.LBB0_619:
	s_add_i32 s2, s22, 1
	s_cmpk_lg_i32 s8, 0xe0
	s_cselect_b32 s12, s3, 0x70
	v_add_u32_e32 v2, s12, v63
	v_lshl_add_u64 v[4:5], s[10:11], 0, v[2:3]
	v_mad_u64_u32 v[6:7], s[12:13], v4, s34, v[58:59]
	v_lshlrev_b64 v[8:9], 7, v[2:3]
	s_waitcnt vmcnt(4)
	v_lshlrev_b32_e32 v86, 16, v31
	v_and_b32_e32 v87, 0xffff0000, v31
	v_mad_i32_i24 v7, v5, s34, v7
	v_lshl_add_u64 v[10:11], v[54:55], 0, v[8:9]
	v_lshl_add_u64 v[12:13], v[56:57], 0, v[8:9]
	v_lshlrev_b32_e32 v84, 16, v35
	v_and_b32_e32 v85, 0xffff0000, v35
	v_pk_mul_f32 v[68:69], v[86:87], v[86:87]
	v_pk_fma_f32 v[88:89], v[84:85], v[84:85], v[68:69]
	s_nop 0
	global_load_dwordx4 v[68:71], v[52:53], off offset:16
	global_load_dwordx4 v[72:75], v[52:53], off
	global_load_dwordx4 v[76:79], v[52:53], off offset:144
	global_load_dwordx4 v[80:83], v[52:53], off offset:128
	global_load_dwordx4 v[20:23], v[6:7], off
	global_load_dwordx4 v[24:27], v[6:7], off offset:64
	s_nop 0
	global_load_dwordx4 v[4:7], v[10:11], off offset:16
	global_load_dwordx4 v[16:19], v[10:11], off
	s_nop 0
	global_load_dwordx4 v[8:11], v[12:13], off offset:16
	s_nop 0
	global_load_dwordx4 v[12:15], v[12:13], off
	v_lshlrev_b32_e32 v92, 16, v33
	v_and_b32_e32 v93, 0xffff0000, v33
	v_lshlrev_b32_e32 v98, 16, v32
	v_and_b32_e32 v99, 0xffff0000, v32
	v_lshlrev_b32_e32 v32, 16, v28
	v_and_b32_e32 v33, 0xffff0000, v28
	v_lshlrev_b32_e32 v94, 16, v29
	v_and_b32_e32 v95, 0xffff0000, v29
	v_pk_mul_f32 v[28:29], v[32:33], v[32:33]
	v_pk_mul_f32 v[96:97], v[94:95], v[94:95]
	v_pk_fma_f32 v[28:29], v[98:99], v[98:99], v[28:29]
	v_lshlrev_b32_e32 v90, 16, v34
	v_and_b32_e32 v91, 0xffff0000, v34
	v_lshlrev_b32_e32 v34, 16, v30
	v_and_b32_e32 v35, 0xffff0000, v30
	v_pk_fma_f32 v[96:97], v[92:93], v[92:93], v[96:97]
	v_add_f32_e32 v1, v28, v29
	v_pk_mul_f32 v[30:31], v[34:35], v[34:35]
	v_add_f32_e32 v1, v96, v1
	v_pk_fma_f32 v[30:31], v[90:91], v[90:91], v[30:31]
	v_add_f32_e32 v1, v97, v1
	v_add_f32_e32 v1, v30, v1
	v_add_f32_e32 v1, v31, v1
	v_add_f32_e32 v1, v88, v1
	v_add_f32_e32 v1, v89, v1
	ds_bpermute_b32 v2, v64, v1
	s_mov_b32 s12, 0xff800000
	s_cmp_gt_u32 s22, 6
	s_waitcnt lgkmcnt(0)
	v_add_f32_e32 v1, v1, v2
	ds_bpermute_b32 v2, v65, v1
	s_waitcnt lgkmcnt(0)
	v_add_f32_e32 v1, v1, v2
	v_fmamk_f32 v1, v1, 0x3c800000, v191
	v_cmp_gt_f32_e64 s[54:55], s71, v1
	v_mul_f32_e32 v2, 0x4b800000, v1
	s_nop 0
	v_cndmask_b32_e64 v1, v1, v2, s[54:55]
	v_rsq_f32_e32 v1, v1
	s_nop 0
	v_mul_f32_e32 v2, 0x45800000, v1
	v_cndmask_b32_e64 v1, v1, v2, s[54:55]
	v_mul_f32_e32 v2, 0x3e38aa3b, v1
	v_pk_mul_f32 v[30:31], v[2:3], v[32:33] op_sel_hi:[0,1]
	v_pk_mul_f32 v[28:29], v[2:3], v[98:99] op_sel_hi:[0,1]
	v_pk_mul_f32 v[34:35], v[2:3], v[34:35] op_sel_hi:[0,1]
	s_waitcnt vmcnt(8)
	v_pk_mul_f32 v[28:29], v[72:73], v[28:29]
	s_waitcnt vmcnt(7)
	v_pk_mul_f32 v[34:35], v[76:77], v[34:35]
	s_waitcnt vmcnt(6)
	v_pk_mul_f32 v[30:31], v[80:81], v[30:31]
	s_nop 0
	v_pk_mul_f32 v[32:33], v[48:49], v[30:31]
	s_nop 0
	v_pk_fma_f32 v[32:33], v[40:41], v[28:29], v[32:33] neg_lo:[0,0,1] neg_hi:[0,0,1]
	v_pk_mul_f32 v[28:29], v[48:49], v[28:29]
	v_cvt_pk_bf16_f32 v32, v32, v33
	v_pk_fma_f32 v[28:29], v[40:41], v[30:31], v[28:29]
	v_pk_mul_f32 v[40:41], v[2:3], v[94:95] op_sel_hi:[0,1]
	v_pk_mul_f32 v[30:31], v[2:3], v[92:93] op_sel_hi:[0,1]
	v_pk_mul_f32 v[40:41], v[82:83], v[40:41]
	v_pk_mul_f32 v[30:31], v[74:75], v[30:31]
	v_pk_mul_f32 v[48:49], v[50:51], v[40:41]
	v_cvt_pk_bf16_f32 v28, v28, v29
	v_pk_fma_f32 v[48:49], v[42:43], v[30:31], v[48:49] neg_lo:[0,0,1] neg_hi:[0,0,1]
	v_pk_mul_f32 v[30:31], v[50:51], v[30:31]
	v_cvt_pk_bf16_f32 v33, v48, v49
	v_pk_fma_f32 v[30:31], v[42:43], v[40:41], v[30:31]
	v_pk_mul_f32 v[40:41], v[2:3], v[90:91] op_sel_hi:[0,1]
	v_pk_mul_f32 v[40:41], v[68:69], v[40:41]
	v_pk_mul_f32 v[42:43], v[44:45], v[34:35]
	v_pk_mul_f32 v[34:35], v[36:37], v[34:35]
	v_pk_fma_f32 v[42:43], v[36:37], v[40:41], v[42:43] neg_lo:[0,0,1] neg_hi:[0,0,1]
	v_pk_fma_f32 v[36:37], v[44:45], v[40:41], v[34:35]
	v_pk_mul_f32 v[40:41], v[2:3], v[86:87] op_sel_hi:[0,1]
	v_pk_mul_f32 v[34:35], v[2:3], v[84:85] op_sel_hi:[0,1]
	v_pk_mul_f32 v[40:41], v[40:41], v[78:79]
	v_pk_mul_f32 v[34:35], v[34:35], v[70:71]
	v_pk_mul_f32 v[44:45], v[46:47], v[40:41]
	v_cvt_pk_bf16_f32 v29, v30, v31
	v_pk_fma_f32 v[44:45], v[38:39], v[34:35], v[44:45] neg_lo:[0,0,1] neg_hi:[0,0,1]
	v_pk_mul_f32 v[38:39], v[38:39], v[40:41]
	v_cvt_pk_bf16_f32 v30, v36, v37
	v_pk_fma_f32 v[38:39], v[46:47], v[34:35], v[38:39]
	v_cvt_pk_bf16_f32 v34, v42, v43
	v_cvt_pk_bf16_f32 v31, v38, v39
	ds_read_b128 v[36:39], v0
	ds_read_b128 v[40:43], v0 offset:64
	v_cvt_pk_bf16_f32 v35, v44, v45
	s_waitcnt lgkmcnt(1)
	s_nop 0
	v_mfma_f32_16x16x32_bf16 v[36:39], v[36:39], v[32:35], 0
	s_waitcnt lgkmcnt(0)
	v_mfma_f32_16x16x32_bf16 v[36:39], v[40:43], v[28:31], v[36:39]
	ds_read_b128 v[42:45], v0 offset:2368
	s_nop 6
	v_cndmask_b32_e64 v2, v204, v37, s[40:41]
	v_cndmask_b32_e64 v37, v204, v38, s[44:45]
	v_cndmask_b32_e64 v46, v204, v39, s[48:49]
	ds_read_b128 v[38:41], v0 offset:2304
	s_waitcnt lgkmcnt(0)
	v_mfma_f32_16x16x32_bf16 v[38:41], v[38:41], v[32:35], 0
	v_cndmask_b32_e64 v1, v204, v36, s[38:39]
	v_max3_f32 v36, v1, s12, v2
	s_cselect_b64 s[12:13], -1, 0
	v_mfma_f32_16x16x32_bf16 v[38:41], v[42:45], v[28:31], v[38:41]
	s_or_b64 s[54:55], s[90:91], s[12:13]
	v_max3_f32 v47, v36, v37, v46
	ds_read_b128 v[42:45], v0 offset:4672
	s_cmp_gt_u32 s22, 5
	s_cselect_b64 s[12:13], -1, 0
	s_nop 2
	v_cndmask_b32_e64 v48, v204, v38, s[54:55]
	v_cndmask_b32_e64 v49, v204, v39, s[54:55]
	v_max3_f32 v38, v47, v48, v49
	v_cndmask_b32_e64 v47, v204, v40, s[54:55]
	v_cndmask_b32_e64 v50, v204, v41, s[54:55]
	v_max3_f32 v51, v38, v47, v50
	ds_read_b128 v[38:41], v0 offset:4608
	s_waitcnt lgkmcnt(0)
	v_mfma_f32_16x16x32_bf16 v[38:41], v[38:41], v[32:35], 0
	s_or_b64 s[54:55], s[90:91], s[12:13]
	s_cmp_gt_u32 s22, 4
	s_cselect_b64 s[12:13], -1, 0
	v_mfma_f32_16x16x32_bf16 v[38:41], v[42:45], v[28:31], v[38:41]
	ds_read_b128 v[42:45], v0 offset:6976
	v_add_u32_e32 v36, 0x900, v0
	s_nop 5
	v_cndmask_b32_e64 v67, v204, v38, s[54:55]
	v_cndmask_b32_e64 v68, v204, v39, s[54:55]
	v_max3_f32 v38, v51, v67, v68
	v_cndmask_b32_e64 v51, v204, v40, s[54:55]
	v_cndmask_b32_e64 v69, v204, v41, s[54:55]
	v_max3_f32 v70, v38, v51, v69
	ds_read_b128 v[38:41], v0 offset:6912
	s_waitcnt lgkmcnt(0)
	v_mfma_f32_16x16x32_bf16 v[38:41], v[38:41], v[32:35], 0
	s_or_b64 s[54:55], s[90:91], s[12:13]
	s_cmp_gt_u32 s22, 3
	s_cselect_b64 s[12:13], -1, 0
	v_mfma_f32_16x16x32_bf16 v[38:41], v[42:45], v[28:31], v[38:41]
	ds_read_b128 v[42:45], v0 offset:9280
	s_nop 6
	v_cndmask_b32_e64 v71, v204, v38, s[54:55]
	v_cndmask_b32_e64 v72, v204, v39, s[54:55]
	v_max3_f32 v38, v70, v71, v72
	v_cndmask_b32_e64 v70, v204, v40, s[54:55]
	v_cndmask_b32_e64 v73, v204, v41, s[54:55]
	v_max3_f32 v74, v38, v70, v73
	ds_read_b128 v[38:41], v0 offset:9216
	s_waitcnt lgkmcnt(0)
	v_mfma_f32_16x16x32_bf16 v[38:41], v[38:41], v[32:35], 0
	s_or_b64 s[54:55], s[90:91], s[12:13]
	s_cmp_gt_u32 s22, 2
	s_cselect_b64 s[12:13], -1, 0
	v_mfma_f32_16x16x32_bf16 v[38:41], v[42:45], v[28:31], v[38:41]
	ds_read_b128 v[42:45], v0 offset:11584
	s_nop 6
	v_cndmask_b32_e64 v75, v204, v38, s[54:55]
	v_cndmask_b32_e64 v76, v204, v39, s[54:55]
	v_max3_f32 v38, v74, v75, v76
	v_cndmask_b32_e64 v74, v204, v40, s[54:55]
	v_cndmask_b32_e64 v77, v204, v41, s[54:55]
	v_max3_f32 v78, v38, v74, v77
	ds_read_b128 v[38:41], v0 offset:11520
	s_waitcnt lgkmcnt(0)
	v_mfma_f32_16x16x32_bf16 v[38:41], v[38:41], v[32:35], 0
	s_or_b64 s[54:55], s[90:91], s[12:13]
	s_cmp_gt_u32 s22, 1
	s_cselect_b64 s[12:13], -1, 0
	v_mfma_f32_16x16x32_bf16 v[38:41], v[42:45], v[28:31], v[38:41]
	ds_read_b128 v[42:45], v0 offset:13888
	s_nop 6
	v_cndmask_b32_e64 v79, v204, v38, s[54:55]
	v_cndmask_b32_e64 v80, v204, v39, s[54:55]
	v_max3_f32 v38, v78, v79, v80
	v_cndmask_b32_e64 v78, v204, v40, s[54:55]
	v_cndmask_b32_e64 v81, v204, v41, s[54:55]
	v_max3_f32 v82, v38, v78, v81
	ds_read_b128 v[38:41], v0 offset:13824
	s_waitcnt lgkmcnt(0)
	v_mfma_f32_16x16x32_bf16 v[38:41], v[38:41], v[32:35], 0
	s_or_b64 s[54:55], s[90:91], s[12:13]
	s_or_b32 s12, s22, s57
	s_cmp_eq_u32 s12, 0
	v_mfma_f32_16x16x32_bf16 v[38:41], v[42:45], v[28:31], v[38:41]
	ds_read_b128 v[42:45], v0 offset:16192
	s_mov_b64 s[12:13], 0xc000
	s_mov_b32 s22, s2
	s_nop 4
	v_cndmask_b32_e64 v83, v204, v38, s[54:55]
	v_cndmask_b32_e64 v84, v204, v39, s[54:55]
	v_max3_f32 v38, v82, v83, v84
	v_cndmask_b32_e64 v82, v204, v40, s[54:55]
	v_cndmask_b32_e64 v85, v204, v41, s[54:55]
	v_max3_f32 v86, v38, v82, v85
	ds_read_b128 v[38:41], v0 offset:16128
	s_waitcnt lgkmcnt(0)
	v_mfma_f32_16x16x32_bf16 v[38:41], v[38:41], v[32:35], 0
	s_cselect_b64 s[54:55], -1, 0
	s_add_i32 s3, s3, 16
	v_mfma_f32_16x16x32_bf16 v[38:41], v[42:45], v[28:31], v[38:41]
	s_nop 7
	v_cndmask_b32_e64 v42, v38, v204, s[54:55]
	v_cndmask_b32_e64 v87, v39, v204, s[54:55]
	v_max3_f32 v38, v86, v42, v87
	v_cndmask_b32_e64 v86, v40, v204, s[54:55]
	v_cndmask_b32_e64 v88, v41, v204, s[54:55]
	v_max3_f32 v43, v38, v86, v88
	ds_read_b128 v[38:41], v0 offset:18432
	s_waitcnt lgkmcnt(0)
	v_mfma_f32_16x16x32_bf16 v[32:35], v[38:41], v[32:35], 0
	ds_read_b128 v[38:41], v0 offset:18496
	s_waitcnt lgkmcnt(0)
	v_mfma_f32_16x16x32_bf16 v[28:31], v[38:41], v[28:31], v[32:35]
	s_nop 7
	v_cndmask_b32_e32 v28, v28, v204, vcc
	v_cndmask_b32_e64 v29, v204, v29, s[50:51]
	v_max3_f32 v0, v43, v28, v29
	v_cndmask_b32_e64 v30, v30, v204, s[42:43]
	v_cndmask_b32_e64 v31, v31, v204, s[46:47]
	v_max3_f32 v0, v0, v30, v31
	ds_bpermute_b32 v32, v64, v0
	s_waitcnt lgkmcnt(0)
	v_max_f32_e32 v32, v32, v32
	v_max_f32_e32 v0, v0, v32
	ds_bpermute_b32 v32, v65, v0
	s_waitcnt lgkmcnt(0)
	v_max3_f32 v32, v0, v32, v62
	v_sub_f32_e32 v0, v1, v32
	v_exp_f32_e32 v89, v0
	v_sub_f32_e32 v1, v2, v32
	v_exp_f32_e32 v90, v1
	v_sub_f32_e32 v1, v37, v32
	v_exp_f32_e32 v91, v1
	v_sub_f32_e32 v1, v46, v32
	v_exp_f32_e32 v92, v1
	v_sub_f32_e32 v1, v48, v32
	v_add_f32_e32 v0, 0, v89
	v_exp_f32_e32 v93, v1
	v_sub_f32_e32 v1, v49, v32
	v_add_f32_e32 v0, v90, v0
	v_exp_f32_e32 v94, v1
	v_sub_f32_e32 v1, v47, v32
	v_add_f32_e32 v0, v91, v0
	v_exp_f32_e32 v95, v1
	v_sub_f32_e32 v1, v50, v32
	v_add_f32_e32 v0, v92, v0
	v_exp_f32_e32 v96, v1
	v_add_f32_e32 v0, v93, v0
	v_add_f32_e32 v0, v94, v0
	v_add_f32_e32 v0, v95, v0
	v_add_f32_e32 v1, v96, v0
	v_sub_f32_e32 v0, v67, v32
	v_exp_f32_e32 v0, v0
	v_sub_f32_e32 v2, v68, v32
	v_exp_f32_e32 v34, v2
	v_sub_f32_e32 v2, v51, v32
	v_exp_f32_e32 v39, v2
	v_sub_f32_e32 v2, v69, v32
	v_exp_f32_e32 v43, v2
	v_sub_f32_e32 v2, v71, v32
	v_add_f32_e32 v1, v0, v1
	v_exp_f32_e32 v47, v2
	v_sub_f32_e32 v2, v72, v32
	v_add_f32_e32 v1, v34, v1
	v_exp_f32_e32 v50, v2
	v_sub_f32_e32 v2, v70, v32
	v_add_f32_e32 v1, v39, v1
	v_exp_f32_e32 v68, v2
	v_sub_f32_e32 v2, v73, v32
	v_add_f32_e32 v1, v43, v1
	v_exp_f32_e32 v71, v2
	v_add_f32_e32 v1, v47, v1
	v_add_f32_e32 v1, v50, v1
	v_add_f32_e32 v1, v68, v1
	v_add_f32_e32 v2, v71, v1
	v_sub_f32_e32 v1, v75, v32
	v_exp_f32_e32 v1, v1
	v_sub_f32_e32 v33, v76, v32
	v_exp_f32_e32 v35, v33
	v_sub_f32_e32 v33, v74, v32
	v_exp_f32_e32 v40, v33
	v_sub_f32_e32 v33, v77, v32
	v_exp_f32_e32 v44, v33
	v_sub_f32_e32 v33, v79, v32
	v_add_f32_e32 v2, v1, v2
	v_exp_f32_e32 v48, v33
	v_sub_f32_e32 v33, v80, v32
	v_add_f32_e32 v2, v35, v2
	v_exp_f32_e32 v51, v33
	v_sub_f32_e32 v33, v78, v32
	v_add_f32_e32 v2, v40, v2
	v_exp_f32_e32 v69, v33
	v_sub_f32_e32 v33, v81, v32
	v_add_f32_e32 v2, v44, v2
	v_exp_f32_e32 v72, v33
	v_add_f32_e32 v2, v48, v2
	v_add_f32_e32 v2, v51, v2
	v_add_f32_e32 v2, v69, v2
	v_add_f32_e32 v33, v72, v2
	v_sub_f32_e32 v2, v83, v32
	v_exp_f32_e32 v2, v2
	v_sub_f32_e32 v37, v84, v32
	v_exp_f32_e32 v37, v37
	v_sub_f32_e32 v38, v82, v32
	v_exp_f32_e32 v41, v38
	v_sub_f32_e32 v38, v85, v32
	v_exp_f32_e32 v45, v38
	v_sub_f32_e32 v38, v42, v32
	v_add_f32_e32 v33, v2, v33
	v_exp_f32_e32 v49, v38
	v_sub_f32_e32 v38, v87, v32
	v_add_f32_e32 v33, v37, v33
	v_exp_f32_e32 v67, v38
	v_sub_f32_e32 v38, v86, v32
	v_add_f32_e32 v33, v41, v33
	v_exp_f32_e32 v70, v38
	v_sub_f32_e32 v38, v88, v32
	v_add_f32_e32 v33, v45, v33
	v_exp_f32_e32 v73, v38
	v_add_f32_e32 v33, v49, v33
	v_add_f32_e32 v33, v67, v33
	v_add_f32_e32 v33, v70, v33
	v_sub_f32_e32 v28, v28, v32
	v_add_f32_e32 v38, v73, v33
	v_exp_f32_e32 v33, v28
	v_sub_f32_e32 v29, v29, v32
	v_add_f32_e32 v28, v33, v38
	v_exp_f32_e32 v38, v29
	v_sub_f32_e32 v29, v30, v32
	v_exp_f32_e32 v42, v29
	v_sub_f32_e32 v29, v31, v32
	v_exp_f32_e32 v46, v29
	v_add_f32_e32 v28, v38, v28
	v_add_f32_e32 v28, v42, v28
	v_cvt_pk_bf16_f32 v30, v93, v94
	v_add_f32_e32 v28, v46, v28
	ds_bpermute_b32 v29, v64, v28
	v_add_u32_e32 v94, s8, v66
	v_add_u32_e32 v74, 0x12000, v94
	v_add_u32_e32 v76, 0x12020, v94
	v_add_u32_e32 v78, 0x14100, v94
	s_waitcnt lgkmcnt(0)
	v_add_f32_e32 v28, v28, v29
	ds_bpermute_b32 v29, v65, v28
	v_add_u32_e32 v80, 0x14120, v94
	v_add_u32_e32 v82, 0x16200, v94
	v_add_u32_e32 v84, 0x16220, v94
	v_add_u32_e32 v86, 0x18300, v94
	s_waitcnt lgkmcnt(0)
	v_add_f32_e32 v28, v28, v29
	v_sub_f32_e32 v29, v62, v32
	v_exp_f32_e32 v29, v29
	v_add_u32_e32 v88, 0x18320, v94
	ds_read_b64 v[74:75], v74
	ds_read_b64 v[76:77], v76
	ds_read_b64 v[78:79], v78
	ds_read_b64 v[80:81], v80
	v_add_f32_e32 v32, v29, v28
	v_cvt_pk_bf16_f32 v28, v89, v90
	ds_read_b64 v[82:83], v82
	ds_read_b64 v[84:85], v84
	ds_read_b64 v[86:87], v86
	ds_read_b64 v[88:89], v88
	v_cvt_pk_bf16_f32 v29, v91, v92
	v_cvt_pk_bf16_f32 v31, v95, v96
	s_add_i32 s8, s8, 32
	s_cmpk_lg_i32 s8, 0x100
	s_waitcnt lgkmcnt(6)
	v_mfma_f32_16x16x32_bf16 v[74:77], v[74:77], v[28:31], 0
	s_waitcnt lgkmcnt(4)
	v_mfma_f32_16x16x32_bf16 v[78:81], v[78:81], v[28:31], 0
	s_waitcnt lgkmcnt(2)
	v_mfma_f32_16x16x32_bf16 v[82:85], v[82:85], v[28:31], 0
	s_waitcnt lgkmcnt(0)
	v_mfma_f32_16x16x32_bf16 v[28:31], v[86:89], v[28:31], 0
	v_cvt_pk_bf16_f32 v86, v0, v34
	v_add_u32_e32 v0, 0x12040, v94
	v_add_u32_e32 v34, 0x12060, v94
	ds_read_b64 v[90:91], v0
	ds_read_b64 v[92:93], v34
	v_cvt_pk_bf16_f32 v87, v39, v43
	v_cvt_pk_bf16_f32 v88, v47, v50
	v_cvt_pk_bf16_f32 v89, v68, v71
	v_add_u32_e32 v0, 0x14140, v94
	v_add_u32_e32 v34, 0x14160, v94
	s_waitcnt lgkmcnt(0)
	v_mfma_f32_16x16x32_bf16 v[74:77], v[90:93], v[86:89], v[74:77]
	ds_read_b64 v[90:91], v0
	ds_read_b64 v[92:93], v34
	v_add_u32_e32 v0, 0x16240, v94
	v_add_u32_e32 v34, 0x16260, v94
	s_waitcnt lgkmcnt(0)
	v_mfma_f32_16x16x32_bf16 v[78:81], v[90:93], v[86:89], v[78:81]
	ds_read_b64 v[90:91], v0
	ds_read_b64 v[92:93], v34
	v_add_u32_e32 v0, 0x18340, v94
	v_add_u32_e32 v34, 0x18360, v94
	s_waitcnt lgkmcnt(0)
	v_mfma_f32_16x16x32_bf16 v[82:85], v[90:93], v[86:89], v[82:85]
	ds_read_b64 v[90:91], v0
	ds_read_b64 v[92:93], v34
	v_add_u32_e32 v0, 0x12080, v94
	s_waitcnt lgkmcnt(0)
	v_mfma_f32_16x16x32_bf16 v[28:31], v[90:93], v[86:89], v[28:31]
	v_cvt_pk_bf16_f32 v86, v1, v35
	v_add_u32_e32 v1, 0x120a0, v94
	ds_read_b64 v[90:91], v0
	ds_read_b64 v[92:93], v1
	v_cvt_pk_bf16_f32 v87, v40, v44
	v_cvt_pk_bf16_f32 v88, v48, v51
	v_cvt_pk_bf16_f32 v89, v69, v72
	v_add_u32_e32 v0, 0x14180, v94
	v_add_u32_e32 v1, 0x141a0, v94
	s_waitcnt lgkmcnt(0)
	v_mfma_f32_16x16x32_bf16 v[74:77], v[90:93], v[86:89], v[74:77]
	ds_read_b64 v[90:91], v0
	ds_read_b64 v[92:93], v1
	v_add_u32_e32 v0, 0x16280, v94
	v_add_u32_e32 v1, 0x162a0, v94
	s_waitcnt lgkmcnt(0)
	v_mfma_f32_16x16x32_bf16 v[78:81], v[90:93], v[86:89], v[78:81]
	ds_read_b64 v[90:91], v0
	ds_read_b64 v[92:93], v1
	v_add_u32_e32 v0, 0x18380, v94
	v_add_u32_e32 v1, 0x183a0, v94
	s_waitcnt lgkmcnt(0)
	v_mfma_f32_16x16x32_bf16 v[82:85], v[90:93], v[86:89], v[82:85]
	ds_read_b64 v[90:91], v0
	ds_read_b64 v[92:93], v1
	v_add_u32_e32 v0, 0x120c0, v94
	v_add_u32_e32 v1, 0x120e0, v94
	s_waitcnt lgkmcnt(0)
	v_mfma_f32_16x16x32_bf16 v[28:31], v[90:93], v[86:89], v[28:31]
	v_cvt_pk_bf16_f32 v88, v49, v67
	ds_read_b64 v[48:49], v0
	ds_read_b64 v[50:51], v1
	v_add_u32_e32 v0, 0x141c0, v94
	v_cvt_pk_bf16_f32 v89, v70, v73
	v_add_u32_e32 v1, 0x141e0, v94
	ds_read_b64 v[68:69], v0
	ds_read_b64 v[70:71], v1
	v_cvt_pk_bf16_f32 v86, v2, v37
	v_cvt_pk_bf16_f32 v87, v41, v45
	v_add_u32_e32 v0, 0x162c0, v94
	v_add_u32_e32 v1, 0x162e0, v94
	s_waitcnt lgkmcnt(2)
	v_mfma_f32_16x16x32_bf16 v[48:51], v[48:51], v[86:89], v[74:77]
	ds_read_b64 v[72:73], v0
	s_nop 1
	ds_read_b64 v[74:75], v1
	v_add_u32_e32 v0, 0x183c0, v94
	v_add_u32_e32 v1, 0x183e0, v94
	s_waitcnt lgkmcnt(2)
	v_mfma_f32_16x16x32_bf16 v[68:71], v[68:71], v[86:89], v[78:81]
	ds_read_b64 v[76:77], v0
	s_nop 1
	ds_read_b64 v[78:79], v1
	v_cvt_pk_bf16_f32 v0, v33, v38
	v_add_u32_e32 v33, 0x12100, v94
	ds_read_b64 v[38:39], v33
	v_add_u32_e32 v33, 0x14200, v94
	v_cvt_pk_bf16_f32 v1, v42, v46
	ds_read_b64 v[42:43], v33
	v_add_u32_e32 v33, 0x16300, v94
	v_mov_b32_e32 v2, v3
	ds_read_b64 v[46:47], v33
	v_add_u32_e32 v33, 0x18400, v94
	s_waitcnt lgkmcnt(1)
	v_mov_b32_e32 v44, v42
	v_mov_b32_e32 v45, v43
	v_mov_b32_e32 v40, v38
	v_mov_b32_e32 v41, v39
	v_mfma_f32_16x16x32_bf16 v[42:45], v[42:45], v[0:3], v[68:71]
	s_nop 2
	ds_read_b64 v[68:69], v33
	s_waitcnt lgkmcnt(0)
	v_mov_b32_e32 v70, v68
	v_mfma_f32_16x16x32_bf16 v[38:41], v[38:41], v[0:3], v[48:51]
	v_mov_b32_e32 v71, v69
	s_nop 1
	v_mov_b32_e32 v48, v46
	v_mov_b32_e32 v49, v47
	v_mfma_f32_16x16x32_bf16 v[72:75], v[72:75], v[86:89], v[82:85]
	v_mfma_f32_16x16x32_bf16 v[28:31], v[76:79], v[86:89], v[28:31]
	v_mfma_f32_16x16x32_bf16 v[46:49], v[46:49], v[0:3], v[72:75]
	v_mfma_f32_16x16x32_bf16 v[28:31], v[68:71], v[0:3], v[28:31]
	v_rcp_f32_e32 v0, v32
	s_nop 0
	v_pk_mul_f32 v[32:33], v[0:1], v[38:39] op_sel_hi:[0,1]
	v_pk_mul_f32 v[34:35], v[0:1], v[40:41] op_sel_hi:[0,1]
	v_cvt_pk_bf16_f32 v32, v32, v33
	v_cvt_pk_bf16_f32 v33, v34, v35
	global_store_dwordx2 v[60:61], v[32:33], off offset:-64
	v_pk_mul_f32 v[32:33], v[0:1], v[42:43] op_sel_hi:[0,1]
	v_pk_mul_f32 v[34:35], v[0:1], v[44:45] op_sel_hi:[0,1]
	v_cvt_pk_bf16_f32 v32, v32, v33
	v_cvt_pk_bf16_f32 v33, v34, v35
	global_store_dwordx2 v[60:61], v[32:33], off offset:-32
	v_pk_mul_f32 v[32:33], v[0:1], v[46:47] op_sel_hi:[0,1]
	v_pk_mul_f32 v[34:35], v[0:1], v[48:49] op_sel_hi:[0,1]
	v_pk_mul_f32 v[28:29], v[0:1], v[28:29] op_sel_hi:[0,1]
	v_pk_mul_f32 v[0:1], v[0:1], v[30:31] op_sel_hi:[0,1]
	v_cvt_pk_bf16_f32 v32, v32, v33
	v_cvt_pk_bf16_f32 v33, v34, v35
	v_cvt_pk_bf16_f32 v28, v28, v29
	v_cvt_pk_bf16_f32 v29, v0, v1
	global_store_dwordx2 v[60:61], v[32:33], off
	global_store_dwordx2 v[60:61], v[28:29], off offset:32
	v_mov_b32_e32 v0, v36
	s_waitcnt vmcnt(4)
	v_mov_b64_e32 v[34:35], v[22:23]
	v_mov_b64_e32 v[30:31], v[26:27]
	v_mov_b64_e32 v[42:43], v[18:19]
	v_mov_b64_e32 v[38:39], v[6:7]
	v_mov_b64_e32 v[50:51], v[14:15]
	v_mov_b64_e32 v[46:47], v[10:11]
	v_lshl_add_u64 v[60:61], v[60:61], 0, s[12:13]
	v_mov_b64_e32 v[32:33], v[20:21]
	v_mov_b64_e32 v[28:29], v[24:25]
	v_mov_b64_e32 v[40:41], v[16:17]
	v_mov_b64_e32 v[36:37], v[4:5]
	v_mov_b64_e32 v[48:49], v[12:13]
	v_mov_b64_e32 v[44:45], v[8:9]
	s_cbranch_scc1 .LBB0_619
	v_readlane_b32 s2, v254, 32
	s_add_i32 s29, s29, s2
	s_add_i32 s28, s28, s2
	s_cmpk_gt_i32 s29, 0xff
	s_mov_b64 s[90:91], s[18:19]
	s_cbranch_scc0 .LBB0_594
	v_readlane_b32 s4, v254, 22
	v_readlane_b32 s6, v254, 24
	v_readlane_b32 s7, v254, 25
	v_readlane_b32 s60, v254, 26
	s_mov_b64 s[66:67], s[6:7]
	v_readlane_b32 s61, v254, 27
	v_readlane_b32 s5, v254, 23
